# P7 M waves: the post-barrier sleep moved behind the issue of their LDS reads (reads overlap the sleep), retuned to 18
# speedup vs baseline: 1.0082x; 1.0011x over previous
; #define LAS __attribute__((address_space(3)))
;     ...
;     const LAS unsigned char* qrow = base + OFF_Q + (16 * ti + l16) * QS + kq * 16;
;     const LAS unsigned char* krow = base + OFF_K + l16 * QS + kq * 16;
;     const LAS unsigned char* srow = lds + OFF_ST + SET * ST_BYTES + l16 * QS + kq * 16;
;     const LAS unsigned char* vrow = base + OFF_VT + l16 * TS;
; #pragma unroll
;     for (int kk = 0; kk < 4; ++kk) { qf[kk] = *(const LAS bf16x8*)(qrow + kk * 64); sb[0][kk] = *(const LAS bf16x8*)(srow + kk * 64); sb[1][kk] = *(const LAS bf16x8*)(srow + 16 * QS + kk * 64); }
; #pragma unroll
;     for (int si = 0; si < 4; ++si)
; #pragma unroll
;         for (int kk = 0; kk < 4; ++kk) kf[si][kk] = *(const LAS bf16x8*)(krow + si * 16 * QS + kk * 64);
; #pragma unroll
;     for (int vh = 0; vh < 2; ++vh)
; #pragma unroll
;         for (int p = 0; p < 2; ++p) { va[vh][p] = *(const LAS u32x2*)(vrow + vh * 16 * TS + kq * 8 + p * 64); vb2[vh][p] = *(const LAS u32x2*)(vrow + vh * 16 * TS + kq * 8 + p * 64 + 32); }
; #pragma unroll
;     for (int kk = 0; kk < 2; ++kk) { vv[0][kk] = *(const LAS bf16x8*)(vrow + kk * 64 + kq * 16); vv[1][kk] = *(const LAS bf16x8*)(vrow + 16 * TS + kk * 64 + kq * 16);
;         kt[0][kk] = *(const LAS bf16x8*)(base + OFF_KT + (32 * ti + l16) * TS + kk * 64 + kq * 16); kt[1][kk] = *(const LAS bf16x8*)(base + OFF_KT + (32 * ti + 16 + l16) * TS + kk * 64 + kq * 16); }
;     dl[0] = *(const LAS f32x4*)(base + OFF_DL + (32 * ti + 4 * kq) * 4); dl[1] = *(const LAS f32x4*)(base + OFF_DL + (32 * ti + 16 + 4 * kq) * 4);
;     __builtin_amdgcn_sched_barrier(0);
;     f32x4 o[2], as[4];
;     o[0] = (f32x4){0.f, 0.f, 0.f, 0.f}; o[1] = o[0];
; #pragma unroll
;     for (int si = 0; si < 4; ++si) as[si] = (f32x4){0.f, 0.f, 0.f, 0.f};
; #pragma unroll
;     for (int kk = 0; kk < 4; ++kk) { o[0] = MFMA16(qf[kk], sb[0][kk], o[0]); o[1] = MFMA16(qf[kk], sb[1][kk], o[1]);
; #pragma unroll
;         for (int si = 0; si < 4; ++si) as[si] = MFMA16(kf[si][kk], qf[kk], as[si]); }
; #pragma unroll
;     for (int ds = 0; ds < 2; ++ds)
; #pragma unroll
;         for (int vh = 0; vh < 2; ++vh) { st[ds][vh] = st[ds][vh] * dl[ds];
; #pragma unroll
;             for (int kk = 0; kk < 2; ++kk) st[ds][vh] = MFMA16(kt[ds][kk], vv[vh][kk], st[ds][vh]); }
;     const int tq = 16 * ti + l16 - 4 * kq;
; #pragma unroll
;     for (int si = 0; si < 4; ++si)
; #pragma unroll
.LBB0_1179:
	v_add_u32_e32 v28, v117, v84
	ds_read_b128 v[100:103], v99
	ds_read_b128 v[104:107], v99 offset:64
	ds_read_b128 v[108:111], v28
	ds_read_b128 v[138:141], v28 offset:64
	ds_read_b128 v[142:145], v28 offset:4352
	ds_read_b128 v[146:149], v28 offset:4416
	ds_read_b128 v[48:51], v99 offset:128
	ds_read_b128 v[24:27], v99 offset:192
	ds_read_b128 v[56:59], v28 offset:128
	ds_read_b128 v[32:35], v28 offset:192
	ds_read_b128 v[150:153], v28 offset:4480
	ds_read_b128 v[52:55], v28 offset:4544
	v_add_u32_e32 v28, v116, v84
	ds_read_b128 v[154:157], v28 offset:17408
	ds_read_b128 v[158:161], v28 offset:17472
	ds_read_b128 v[162:165], v28 offset:17536
	ds_read_b128 v[60:63], v28 offset:17600
	ds_read_b128 v[166:169], v28 offset:21760
	ds_read_b128 v[170:173], v28 offset:21824
	ds_read_b128 v[174:177], v28 offset:21888
	ds_read_b128 v[64:67], v28 offset:21952
	ds_read_b128 v[178:181], v28 offset:26112
	ds_read_b128 v[182:185], v28 offset:26176
	ds_read_b128 v[186:189], v28 offset:26240
	ds_read_b128 v[68:71], v28 offset:26304
	ds_read_b128 v[190:193], v28 offset:30464
	ds_read_b128 v[194:197], v28 offset:30528
	ds_read_b128 v[76:79], v28 offset:30592
	ds_read_b128 v[72:75], v28 offset:30656
	v_add_u32_e32 v36, v118, v119
	v_add_u32_e32 v28, 0xd000, v36
	v_add_u32_e32 v36, 0xd800, v36
	v_add_u32_e32 v112, v118, v84
	ds_read2_b64 v[40:43], v28 offset1:4
	ds_read2_b64 v[28:31], v28 offset0:8 offset1:12
	ds_read2_b64 v[44:47], v36 offset0:32 offset1:36
	ds_read2_b64 v[36:39], v36 offset0:40 offset1:44
	v_add_u32_e32 v113, v115, v89
	ds_read_b128 v[202:205], v112 offset:53248
	ds_read_b128 v[208:211], v112 offset:53312
	ds_read_b128 v[212:215], v112 offset:55552
	ds_read_b128 v[216:219], v112 offset:55616
	ds_read_b128 v[220:223], v113 offset:34816
	ds_read_b128 v[224:227], v113 offset:34880
	ds_read_b128 v[228:231], v113 offset:37120
	ds_read_b128 v[232:235], v113 offset:37184
	ds_read_b128 v[236:239], v95 offset:57856
	ds_read_b128 v[240:243], v95 offset:57920
	s_add_i32 s3, s3, 2
	s_sleep 18
	s_waitcnt lgkmcnt(14)
	v_mfma_f32_16x16x32_bf16 v[142:145], v[142:145], v[100:103], 0
	s_waitcnt lgkmcnt(1)
	v_pk_mul_f32 v[20:21], v[20:21], v[236:237]
	v_pk_mul_f32 v[22:23], v[22:23], v[238:239]
	v_pk_mul_f32 v[8:9], v[8:9], v[236:237]
	v_mfma_f32_16x16x32_bf16 v[154:157], v[154:157], v[100:103], 0
	v_mul_f32_e64 v10, v10, v238
	v_mul_f32_e64 v11, v11, v239
	s_waitcnt lgkmcnt(0)
	v_pk_mul_f32 v[16:17], v[16:17], v[240:241]
	v_pk_mul_f32 v[18:19], v[18:19], v[242:243]
	v_mfma_f32_16x16x32_bf16 v[166:169], v[166:169], v[100:103], 0
	v_mul_f32_e64 v12, v12, v240
	v_mul_f32_e64 v13, v13, v241
	v_pk_mul_f32 v[14:15], v[14:15], v[242:243]
	s_movk_i32 s0, 0x1000
	v_mfma_f32_16x16x32_bf16 v[178:181], v[178:181], v[100:103], 0
	v_add_co_u32_e32 v112, vcc, s0, v92
	s_movk_i32 s0, 0x3000
	v_mfma_f32_16x16x32_bf16 v[190:193], v[190:193], v[100:103], 0
	v_addc_co_u32_e32 v113, vcc, 0, v93, vcc
	v_mfma_f32_16x16x32_bf16 v[100:103], v[108:111], v[100:103], 0
	v_mfma_f32_16x16x32_bf16 v[108:111], v[220:223], v[212:215], v[20:23]
	v_mfma_f32_16x16x32_bf16 v[142:145], v[146:149], v[104:107], v[142:145]
	v_mfma_f32_16x16x32_bf16 v[146:149], v[158:161], v[104:107], v[154:157]
	v_mfma_f32_16x16x32_bf16 v[154:157], v[170:173], v[104:107], v[166:169]
	v_mfma_f32_16x16x32_bf16 v[8:11], v[220:223], v[202:205], v[8:11]
	v_mfma_f32_16x16x32_bf16 v[202:205], v[228:231], v[202:205], v[16:19]
	v_mfma_f32_16x16x32_bf16 v[158:161], v[182:185], v[104:107], v[178:181]
	v_mfma_f32_16x16x32_bf16 v[166:169], v[194:197], v[104:107], v[190:193]
	v_mfma_f32_16x16x32_bf16 v[100:103], v[138:141], v[104:107], v[100:103]
	v_mfma_f32_16x16x32_bf16 v[16:19], v[224:227], v[216:219], v[108:111]
	v_mfma_f32_16x16x32_bf16 v[108:111], v[162:165], v[48:51], v[146:149]
	v_mfma_f32_16x16x32_bf16 v[138:141], v[174:177], v[48:51], v[154:157]
	s_nop 1
	v_add_co_u32_e32 v146, vcc, s67, v92
	v_mfma_f32_16x16x32_bf16 v[212:215], v[228:231], v[212:215], v[12:15]
	s_nop 0
	v_addc_co_u32_e32 v147, vcc, 0, v93, vcc
	v_add_co_u32_e32 v148, vcc, s0, v92
	v_mfma_f32_16x16x32_bf16 v[104:107], v[150:153], v[48:51], v[142:145]
	v_add_u32_e32 v152, v121, v94
	s_min_u32 s0, s3, 0x7c
	s_lshl_b32 s48, s0, 18
	v_mfma_f32_16x16x32_bf16 v[142:145], v[186:189], v[48:51], v[158:161]
	v_addc_co_u32_e32 v149, vcc, 0, v93, vcc
	v_lshl_add_u64 v[150:151], v[90:91], 0, s[48:49]
	v_mfma_f32_16x16x32_bf16 v[76:79], v[76:79], v[48:51], v[166:169]
	s_mov_b32 s0, 0xc0000
	v_add_co_u32_e32 v150, vcc, s0, v150
	v_mfma_f32_16x16x32_bf16 v[48:51], v[56:59], v[48:51], v[100:103]
	s_nop 0
	v_addc_co_u32_e32 v151, vcc, 0, v151, vcc
	v_mfma_f32_16x16x32_bf16 v[56:59], v[60:63], v[24:27], v[108:111]
	v_cvt_pk_bf16_f32 v102, v16, v17
	v_cvt_pk_bf16_f32 v103, v18, v19
	v_mfma_f32_16x16x32_bf16 v[60:63], v[64:67], v[24:27], v[138:141]
	v_mfma_f32_16x16x32_bf16 v[20:23], v[224:227], v[208:211], v[8:11]
	s_nop 3
	v_cndmask_b32_e64 v58, v58, 0, s[20:21]
	s_nop 1
	v_cndmask_b32_e64 v62, v62, 0, s[28:29]
	v_cndmask_b32_e64 v60, v60, 0, s[24:25]
	v_mfma_f32_16x16x32_bf16 v[8:11], v[232:235], v[216:219], v[212:215]
	v_cndmask_b32_e64 v56, v56, 0, s[64:65]
	v_cvt_pk_bf16_f32 v100, v20, v21
	v_cvt_pk_bf16_f32 v101, v22, v23
	v_mfma_f32_16x16x32_bf16 v[52:55], v[52:55], v[24:27], v[104:107]
	v_mfma_f32_16x16x32_bf16 v[64:67], v[68:71], v[24:27], v[142:145]
	s_nop 2
	v_cvt_pk_bf16_f32 v106, v8, v9
	v_cvt_pk_bf16_f32 v107, v10, v11
	v_mfma_f32_16x16x32_bf16 v[68:71], v[72:75], v[24:27], v[76:79]
	v_mfma_f32_16x16x32_bf16 v[24:27], v[32:35], v[24:27], v[48:51]
	v_cndmask_b32_e64 v35, v63, 0, s[30:31]
	v_cndmask_b32_e64 v34, v61, 0, s[26:27]
	v_cndmask_b32_e64 v33, v59, 0, s[22:23]
	v_cndmask_b32_e64 v32, v57, 0, s[16:17]
	v_mfma_f32_16x16x32_bf16 v[12:15], v[232:235], v[208:211], v[202:205]
	v_cvt_pk_bf16_f32 v32, v56, v32
	v_cvt_pk_bf16_f32 v33, v58, v33
	v_cvt_pk_bf16_f32 v34, v60, v34
	v_cvt_pk_bf16_f32 v35, v62, v35
	v_cndmask_b32_e64 v48, v69, 0, s[44:45]
	s_nop 2
	v_cvt_pk_bf16_f32 v104, v12, v13
	v_cvt_pk_bf16_f32 v105, v14, v15
	ds_write_b64 v152, v[100:101]
	ds_write_b64 v152, v[102:103] offset:4352
	ds_write_b64 v96, v[104:105]
	ds_write_b64 v96, v[106:107] offset:4352
	s_waitcnt vmcnt(3)
; __device__ __forceinline__ unsigned cvtpk_s(float lo, float hi) { f32x2_t v = {lo, hi}; bf16x2_t b = __builtin_convertvector(v, bf16x2_t); return __builtin_bit_cast(unsigned, b); }
; #define HBAR() do { asm volatile("s_waitcnt lgkmcnt(0)" ::: "memory"); __builtin_amdgcn_s_barrier(); asm volatile("" ::: "memory"); } while (0)
; #define MFMA16(a, b, c) __builtin_amdgcn_mfma_f32_16x16x32_bf16((a), (b), (c), 0, 0, 0)
;     ...
;     for (int p = 0; p < 2; ++p) {
;         u32x4 pw; pw.x = cvtpk_s(as[2 * p][0], as[2 * p][1]); pw.y = cvtpk_s(as[2 * p][2], as[2 * p][3]); pw.z = cvtpk_s(as[2 * p + 1][0], as[2 * p + 1][1]); pw.w = cvtpk_s(as[2 * p + 1][2], as[2 * p + 1][3]);
; #pragma unroll
;         for (int vh = 0; vh < 2; ++vh) { const u32x4 vw = {va[vh][p].x, va[vh][p].y, vb2[vh][p].x, vb2[vh][p].y};
;             o[vh] = MFMA16(__builtin_bit_cast(bf16x8, pw), __builtin_bit_cast(bf16x8, vw), o[vh]); }
;     }
;     if ((VAR & 1) == 0 || o[0][0] == 12345.678f) {
; #pragma unroll
;     for (int vh = 0; vh < 2; ++vh)
; #pragma unroll
;         for (int j = 0; j < 4; ++j) *(bf16r*)(ob + (size_t)j * DM * 2 + vh * 32 + ol) = (bf16r)(cvtpk_s(o[vh][j], 0.f) & 0xffffu);
;     }
;     ...
;             hgV<1>(lds, vB, mt); vB = *(const u32x4*)(vp + (size_t)(c + 3 < NC ? c + 3 : NC - 1) * 64 * DM);
;             HBAR();
;             if ((VAR & 4) == 0) hgM<1, VAR>(lds, st, ti, lane, ob + (size_t)(c + 1) * 64 * DM * 2, ol);
	ds_write_b16 v136, v0
	ds_write_b16_d16_hi v136, v0 offset:144
	ds_write_b16 v136, v1 offset:288
	ds_write_b16_d16_hi v136, v1 offset:432
	ds_write_b16 v136, v2 offset:576
	v_cndmask_b32_e64 v0, v71, 0, s[14:15]
	v_cndmask_b32_e64 v1, v70, 0, s[46:47]
	v_cndmask_b32_e64 v49, v68, 0, s[42:43]
	v_cndmask_b32_e64 v50, v67, 0, s[40:41]
	v_cndmask_b32_e64 v51, v66, 0, s[38:39]
	v_cndmask_b32_e64 v65, v65, 0, s[36:37]
	v_cndmask_b32_e64 v64, v64, 0, s[34:35]
	v_mfma_f32_16x16x32_bf16 v[24:27], v[40:43], v[32:35], v[24:27]
	v_cvt_pk_bf16_f32 v40, v64, v65
	v_cvt_pk_bf16_f32 v41, v51, v50
	v_cvt_pk_bf16_f32 v42, v49, v48
	v_cvt_pk_bf16_f32 v43, v1, v0
	v_mfma_f32_16x16x32_bf16 v[32:35], v[44:47], v[32:35], v[52:55]
	ds_write_b16_d16_hi v136, v2 offset:720
	ds_write_b16 v136, v3 offset:864
	ds_write_b16_d16_hi v136, v3 offset:1008
	v_mfma_f32_16x16x32_bf16 v[24:27], v[28:31], v[40:43], v[24:27]
	v_mfma_f32_16x16x32_bf16 v[0:3], v[36:39], v[40:43], v[32:35]
	s_nop 6
	v_cvt_pk_bf16_f32 v24, v24, v25
	v_cvt_pk_bf16_f32 v25, v26, v27
	v_cvt_pk_bf16_f32 v26, v0, v1
	v_cvt_pk_bf16_f32 v27, v2, v3
	global_store_dwordx2 v[244:245], v[24:25], off
	global_store_dwordx2 v[244:245], v[26:27], off offset:32
	global_load_dwordx4 v[0:3], v[150:151], off
	v_add_u32_e32 v25, v122, v119
	v_add_u32_e32 v24, v121, v84
	v_add_u32_e32 v26, 0x800, v25
	s_waitcnt lgkmcnt(0)
	s_barrier
	v_add_u32_e32 v112, v122, v84
	v_add_u32_e32 v113, 0x1c600, v95
	ds_read_b128 v[100:103], v99 offset:58368
	ds_read_b128 v[104:107], v99 offset:58432
	ds_read_b128 v[108:111], v24
	ds_read_b128 v[138:141], v24 offset:64
	ds_read_b128 v[142:145], v24 offset:4352
	ds_read_b128 v[146:149], v24 offset:4416
	ds_read_b128 v[68:71], v99 offset:58496
	ds_read_b128 v[36:39], v99 offset:58560
	ds_read_b128 v[72:75], v24 offset:128
	ds_read_b128 v[44:47], v24 offset:192
	ds_read_b128 v[150:153], v24 offset:4480
	ds_read_b128 v[48:51], v24 offset:4544
	ds_read_b128 v[154:157], v137
	ds_read_b128 v[158:161], v137 offset:64
	ds_read_b128 v[162:165], v137 offset:128
	ds_read_b128 v[52:55], v137 offset:192
	ds_read_b128 v[166:169], v137 offset:4352
	ds_read_b128 v[170:173], v137 offset:4416
	ds_read_b128 v[174:177], v137 offset:4480
	ds_read_b128 v[56:59], v137 offset:4544
	ds_read_b128 v[178:181], v137 offset:8704
	ds_read_b128 v[182:185], v137 offset:8768
	ds_read_b128 v[186:189], v137 offset:8832
	ds_read_b128 v[60:63], v137 offset:8896
	ds_read_b128 v[190:193], v137 offset:13056
	ds_read_b128 v[194:197], v137 offset:13120
	ds_read_b128 v[76:79], v137 offset:13184
	ds_read_b128 v[64:67], v137 offset:13248
	ds_read2_b64 v[40:43], v25 offset1:4
	ds_read2_b64 v[28:31], v25 offset0:8 offset1:12
	ds_read2_b64 v[32:35], v26 offset0:32 offset1:36
	ds_read2_b64 v[24:27], v26 offset0:40 offset1:44
	ds_read_b128 v[202:205], v112
	ds_read_b128 v[208:211], v112 offset:64
	ds_read_b128 v[212:215], v112 offset:2304
	ds_read_b128 v[216:219], v112 offset:2368
	ds_read_b128 v[220:223], v97
	ds_read_b128 v[224:227], v97 offset:64
	ds_read_b128 v[228:231], v97 offset:2304
	ds_read_b128 v[232:235], v97 offset:2368
	ds_read_b128 v[236:239], v113
	ds_read_b128 v[240:243], v113 offset:64
	s_sleep 18
	s_waitcnt lgkmcnt(14)
	v_mfma_f32_16x16x32_bf16 v[142:145], v[142:145], v[100:103], 0
	s_waitcnt lgkmcnt(1)
	v_pk_mul_f32 v[22:23], v[22:23], v[238:239]
	v_pk_mul_f32 v[20:21], v[20:21], v[236:237]
	v_pk_mul_f32 v[18:19], v[18:19], v[238:239]
	v_mfma_f32_16x16x32_bf16 v[154:157], v[154:157], v[100:103], 0
	v_mul_f32_e64 v16, v16, v236
	v_mul_f32_e64 v17, v17, v237
	s_waitcnt lgkmcnt(0)
; __device__ __forceinline__ unsigned cvtpk_s(float lo, float hi) { f32x2_t v = {lo, hi}; bf16x2_t b = __builtin_convertvector(v, bf16x2_t); return __builtin_bit_cast(unsigned, b); }
; #define HBAR() do { asm volatile("s_waitcnt lgkmcnt(0)" ::: "memory"); __builtin_amdgcn_s_barrier(); asm volatile("" ::: "memory"); } while (0)
; #define MFMA16(a, b, c) __builtin_amdgcn_mfma_f32_16x16x32_bf16((a), (b), (c), 0, 0, 0)
;     ...
;     for (int kk = 0; kk < 4; ++kk) { o[0] = MFMA16(qf[kk], sb[0][kk], o[0]); o[1] = MFMA16(qf[kk], sb[1][kk], o[1]);
; #pragma unroll
;         for (int si = 0; si < 4; ++si) as[si] = MFMA16(kf[si][kk], qf[kk], as[si]); }
; #pragma unroll
;     for (int ds = 0; ds < 2; ++ds)
; #pragma unroll
;         for (int vh = 0; vh < 2; ++vh) { st[ds][vh] = st[ds][vh] * dl[ds];
; #pragma unroll
;             for (int kk = 0; kk < 2; ++kk) st[ds][vh] = MFMA16(kt[ds][kk], vv[vh][kk], st[ds][vh]); }
;     const int tq = 16 * ti + l16 - 4 * kq;
; #pragma unroll
;     for (int si = 0; si < 4; ++si)
; #pragma unroll
;         for (int j = 0; j < 4; ++j) if (16 * si + j > tq) as[si][j] = 0.f;
; #pragma unroll
;     for (int p = 0; p < 2; ++p) {
;         u32x4 pw; pw.x = cvtpk_s(as[2 * p][0], as[2 * p][1]); pw.y = cvtpk_s(as[2 * p][2], as[2 * p][3]); pw.z = cvtpk_s(as[2 * p + 1][0], as[2 * p + 1][1]); pw.w = cvtpk_s(as[2 * p + 1][2], as[2 * p + 1][3]);
; #pragma unroll
;         for (int vh = 0; vh < 2; ++vh) { const u32x4 vw = {va[vh][p].x, va[vh][p].y, vb2[vh][p].x, vb2[vh][p].y};
;             o[vh] = MFMA16(__builtin_bit_cast(bf16x8, pw), __builtin_bit_cast(bf16x8, vw), o[vh]); }
;     }
;     if ((VAR & 1) == 0 || o[0][0] == 12345.678f) {
; #pragma unroll
;     for (int vh = 0; vh < 2; ++vh)
; #pragma unroll
;         for (int j = 0; j < 4; ++j) *(bf16r*)(ob + (size_t)j * DM * 2 + vh * 32 + ol) = (bf16r)(cvtpk_s(o[vh][j], 0.f) & 0xffffu);
;     }
;     ...
;             if ((VAR & 4) == 0) hgM<1, VAR>(lds, st, ti, lane, ob + (size_t)(c + 1) * 64 * DM * 2, ol);
;             hgV<0>(lds, vA, mt); vA = *(const u32x4*)(vp + (size_t)(c + 4 < NC ? c + 4 : NC - 1) * 64 * DM);
;             HBAR();
	v_pk_mul_f32 v[14:15], v[14:15], v[242:243]
	v_pk_mul_f32 v[12:13], v[12:13], v[240:241]
	v_mfma_f32_16x16x32_bf16 v[166:169], v[166:169], v[100:103], 0
	v_mul_f32_e64 v10, v10, v242
	v_mul_f32_e64 v11, v11, v243
	v_pk_mul_f32 v[8:9], v[8:9], v[240:241]
	s_mov_b32 s0, 0x40000
	v_mfma_f32_16x16x32_bf16 v[178:181], v[178:181], v[100:103], 0
	v_add_co_u32_e32 v112, vcc, s0, v92
	s_mov_b32 s0, 0x42000
	v_mfma_f32_16x16x32_bf16 v[190:193], v[190:193], v[100:103], 0
	v_addc_co_u32_e32 v113, vcc, 0, v93, vcc
	v_mfma_f32_16x16x32_bf16 v[100:103], v[108:111], v[100:103], 0
	v_mfma_f32_16x16x32_bf16 v[20:23], v[220:223], v[202:205], v[20:23]
	v_mfma_f32_16x16x32_bf16 v[16:19], v[220:223], v[212:215], v[16:19]
	v_mfma_f32_16x16x32_bf16 v[12:15], v[228:231], v[202:205], v[12:15]
	v_mfma_f32_16x16x32_bf16 v[108:111], v[228:231], v[212:215], v[8:11]
	v_mfma_f32_16x16x32_bf16 v[142:145], v[146:149], v[104:107], v[142:145]
	v_mfma_f32_16x16x32_bf16 v[146:149], v[158:161], v[104:107], v[154:157]
	v_mfma_f32_16x16x32_bf16 v[154:157], v[170:173], v[104:107], v[166:169]
	v_mfma_f32_16x16x32_bf16 v[158:161], v[182:185], v[104:107], v[178:181]
	v_mfma_f32_16x16x32_bf16 v[166:169], v[194:197], v[104:107], v[190:193]
	v_mfma_f32_16x16x32_bf16 v[100:103], v[138:141], v[104:107], v[100:103]
	v_mfma_f32_16x16x32_bf16 v[8:11], v[224:227], v[208:211], v[20:23]
	v_mfma_f32_16x16x32_bf16 v[20:23], v[224:227], v[216:219], v[16:19]
	v_mfma_f32_16x16x32_bf16 v[16:19], v[232:235], v[208:211], v[12:15]
	v_mfma_f32_16x16x32_bf16 v[12:15], v[232:235], v[216:219], v[108:111]
	v_mfma_f32_16x16x32_bf16 v[108:111], v[162:165], v[68:71], v[146:149]
	v_mfma_f32_16x16x32_bf16 v[138:141], v[174:177], v[68:71], v[154:157]
	v_mfma_f32_16x16x32_bf16 v[104:107], v[150:153], v[68:71], v[142:145]
	s_nop 1
	v_add_u32_e32 v154, v117, v94
	v_add_co_u32_e32 v150, vcc, s70, v92
	v_mfma_f32_16x16x32_bf16 v[142:145], v[186:189], v[68:71], v[158:161]
	s_nop 0
	v_addc_co_u32_e32 v151, vcc, 0, v93, vcc
	v_add_co_u32_e32 v146, vcc, s0, v92
	v_mfma_f32_16x16x32_bf16 v[76:79], v[76:79], v[68:71], v[166:169]
	s_nop 0
	v_addc_co_u32_e32 v147, vcc, 0, v93, vcc
	s_min_u32 s0, s3, 0x7b
	v_mfma_f32_16x16x32_bf16 v[68:71], v[72:75], v[68:71], v[100:103]
	v_cvt_pk_bf16_f32 v72, v8, v9
	v_cvt_pk_bf16_f32 v73, v10, v11
	v_cvt_pk_bf16_f32 v74, v20, v21
	v_mfma_f32_16x16x32_bf16 v[52:55], v[52:55], v[36:39], v[108:111]
	v_cvt_pk_bf16_f32 v102, v12, v13
	v_cvt_pk_bf16_f32 v103, v14, v15
	v_cvt_pk_bf16_f32 v75, v22, v23
	v_mfma_f32_16x16x32_bf16 v[56:59], v[56:59], v[36:39], v[138:141]
	v_cvt_pk_bf16_f32 v100, v16, v17
	s_nop 2
	v_cndmask_b32_e64 v54, v54, 0, s[20:21]
	v_cndmask_b32_e64 v52, v52, 0, s[64:65]
	v_mfma_f32_16x16x32_bf16 v[48:51], v[48:51], v[36:39], v[104:107]
	v_cvt_pk_bf16_f32 v101, v18, v19
	v_cndmask_b32_e64 v58, v58, 0, s[28:29]
	v_cndmask_b32_e64 v56, v56, 0, s[24:25]
	v_mfma_f32_16x16x32_bf16 v[60:63], v[60:63], v[36:39], v[142:145]
	ds_write_b64 v154, v[72:73]
	ds_write_b64 v154, v[74:75] offset:4352
	ds_write_b64 v98, v[100:101]
	ds_write_b64 v98, v[102:103] offset:4352
	s_waitcnt vmcnt(3)
	ds_write_b16 v135, v4 offset:53248
	ds_write_b16_d16_hi v135, v4 offset:53392
	ds_write_b16 v135, v5 offset:53536
	ds_write_b16_d16_hi v135, v5 offset:53680
	ds_write_b16 v135, v6 offset:53824
	v_mfma_f32_16x16x32_bf16 v[64:67], v[64:67], v[36:39], v[76:79]
	v_cndmask_b32_e64 v63, v63, 0, s[40:41]
	v_cndmask_b32_e64 v62, v62, 0, s[38:39]
	v_cndmask_b32_e64 v61, v61, 0, s[36:37]
	v_mfma_f32_16x16x32_bf16 v[36:39], v[44:47], v[36:39], v[68:71]
	v_cndmask_b32_e64 v47, v59, 0, s[30:31]
	v_cndmask_b32_e64 v46, v57, 0, s[26:27]
	v_cndmask_b32_e64 v45, v55, 0, s[22:23]
	v_cndmask_b32_e64 v44, v53, 0, s[16:17]
	v_cvt_pk_bf16_f32 v44, v52, v44
	v_cvt_pk_bf16_f32 v45, v54, v45
	v_cvt_pk_bf16_f32 v46, v56, v46
	v_cvt_pk_bf16_f32 v47, v58, v47
	v_cndmask_b32_e64 v4, v67, 0, s[14:15]
	v_cndmask_b32_e64 v5, v66, 0, s[46:47]
	v_cndmask_b32_e64 v65, v65, 0, s[44:45]
	v_cndmask_b32_e64 v64, v64, 0, s[42:43]
	v_cndmask_b32_e64 v60, v60, 0, s[34:35]
	v_mfma_f32_16x16x32_bf16 v[36:39], v[40:43], v[44:47], v[36:39]
	v_cvt_pk_bf16_f32 v40, v60, v61
	v_cvt_pk_bf16_f32 v41, v62, v63
	v_cvt_pk_bf16_f32 v42, v64, v65
	v_cvt_pk_bf16_f32 v43, v5, v4
	v_mfma_f32_16x16x32_bf16 v[32:35], v[32:35], v[44:47], v[48:51]
	ds_write_b16_d16_hi v135, v6 offset:53968
	ds_write_b16 v135, v7 offset:54112
	ds_write_b16_d16_hi v135, v7 offset:54256
	v_add_co_u32_e32 v148, vcc, s71, v92
	v_mfma_f32_16x16x32_bf16 v[28:31], v[28:31], v[40:43], v[36:39]
	s_lshl_b32 s48, s0, 18
	v_addc_co_u32_e32 v149, vcc, 0, v93, vcc
	v_mfma_f32_16x16x32_bf16 v[4:7], v[24:27], v[40:43], v[32:35]
	v_lshl_add_u64 v[152:153], v[90:91], 0, s[48:49]
	v_add_co_u32_e32 v152, vcc, 0x100000, v152
	s_nop 2
	v_cvt_pk_bf16_f32 v24, v28, v29
	v_addc_co_u32_e32 v153, vcc, 0, v153, vcc
	v_cvt_pk_bf16_f32 v25, v30, v31
	v_cvt_pk_bf16_f32 v26, v4, v5
	v_cvt_pk_bf16_f32 v27, v6, v7
	global_store_dwordx2 v[246:247], v[24:25], off
	global_store_dwordx2 v[246:247], v[26:27], off offset:32
	global_load_dwordx4 v[4:7], v[152:153], off
	s_waitcnt lgkmcnt(0)
	s_barrier
	s_mov_b64 s[0:1], 0x80000
	s_cmpk_lt_u32 s3, 0x7e
	v_lshl_add_u64 v[92:93], v[92:93], 0, s[0:1]
	v_lshl_add_u64 v[244:245], v[244:245], 0, s[0:1]
	v_lshl_add_u64 v[246:247], v[246:247], 0, s[0:1]
	s_cbranch_scc1 .LBB0_1179
	s_mov_b64 s[16:17], 0
